# classification loop v3: fewer instructions (single mad for address, index reg as loop counter); same list order
# baseline (speedup 1.0000x reference)
; __device__ __forceinline__ void lds_fence() { asm volatile("s_waitcnt lgkmcnt(0)" ::: "memory"); }
; __device__ __forceinline__ unsigned fkey(float s) { const unsigned u = __float_as_uint(s); return (u & 0x80000000u) ? ~u : (u | 0x80000000u); }
; template <bool DUMMY> __device__ __forceinline__ void phase_dsa(const Args& a, unsigned char* lds) {
;     ...
;                     int cs = 0, cc = 0;
;                     for (int i0 = beg + lane * 4; i0 < end; i0 += 256) { const f32x4 v = *(const f32x4*)(sc + i0);
; #pragma unroll
;                         for (int e = 0; e < 4; ++e) { const unsigned k = fkey(v[e]); const unsigned kb = k >> 21;
;                             const bool sure = kb > b1, cand = (kb == b1) && store_c;
;                             const unsigned long long ms = __ballot(sure), mc = __ballot(cand);
;                             if (ms) { const int p = cs + __popcll(ms & ltmask); const int pp = hf ? nsure - 1 - p : p; if (sure && pp >= 0 && pp < 256) list[pp] = i0 + e; cs += __popcll(ms); }
;                             if (mc) { const int p = cc + __popcll(mc & ltmask); const int pp = hf ? c1 - 1 - p : p; if (cand && pp >= 0 && pp < CAP) { hist[2 * pp] = k; hist[2 * pp + 1] = (unsigned)(i0 + e); } cc += __popcll(mc); } } }
;                     lds_fence(); __builtin_amdgcn_s_barrier();
.LBB0_917:
	s_or_b64 exec, exec, s[0:1]
	v_lshlrev_b64 v[10:11], v222, -1
	s_waitcnt lgkmcnt(0)
	s_lshr_b32 s0, s12, 1
	v_not_b32_e32 v120, v10
	v_lshlrev_b32_e32 v10, 2, v222
	s_lshl_b32 s65, s61, 10
	v_not_b32_e32 v8, v11
	v_cmp_gt_u32_e32 vcc, s0, v10
	s_barrier
	s_and_saveexec_b64 s[12:13], vcc
	s_cbranch_execz .LBB0_952
	s_add_i32 s25, s65, 0
	s_mul_i32 s10, s8, s0
	s_add_i32 s25, s25, 0x24080
	s_add_i32 s26, s10, s0
	s_cmp_eq_u32 s8, 0
	s_mul_i32 s1, s61, 0x8020
	s_cselect_b64 s[8:9], -1, 0
	s_lshl_b32 s0, s10, 2
	s_add_i32 s0, s0, s1
	s_add_i32 s0, s0, 0
	v_cmp_gt_i32_e64 s[6:7], s42, v131
	v_add_u32_e32 v11, s10, v10
	s_mov_b32 s27, 0
	v_add_u32_e32 v133, s0, v129
	s_mov_b64 s[14:15], 0
	s_mov_b32 s28, 0
	v_cndmask_b32_e64 v12, -4, 4, s[8:9]
	v_cndmask_b32_e64 v48, -8, 8, s[8:9]
	v_sub_u32_e32 v13, 0xff, v132
	v_add_u32_e32 v14, -1, v131
	v_cndmask_b32_e64 v13, v13, 0, s[8:9]
	v_cndmask_b32_e64 v14, v14, 0, s[8:9]
	v_lshl_add_u32 v13, v13, 2, s25
	v_lshl_add_u32 v14, v14, 3, s23
	v_bfrev_b32_e32 v15, 1
	v_mov_b32_e32 v41, v11
	ds_read_b128 v[20:23], v133
	s_waitcnt lgkmcnt(0)
.Lcls_loop:
	v_mov_b64_e32 v[16:17], v[20:21]
	v_mov_b64_e32 v[18:19], v[22:23]
	s_mov_b64 s[14:15], exec
	v_add_u32_e32 v133, 0x400, v133
	ds_read_b128 v[20:23], v133
	v_add_u32_e32 v43, 1, v41
	v_add_u32_e32 v45, 2, v41
	v_add_u32_e32 v47, 3, v41
	v_ashrrev_i32_e32 v24, 31, v16
	v_ashrrev_i32_e32 v25, 31, v17
	v_ashrrev_i32_e32 v26, 31, v18
	v_ashrrev_i32_e32 v27, 31, v19
	v_or_b32_e32 v24, v15, v24
	v_or_b32_e32 v25, v15, v25
	v_or_b32_e32 v26, v15, v26
	v_or_b32_e32 v27, v15, v27
	v_xor_b32_e32 v40, v16, v24
	v_xor_b32_e32 v42, v17, v25
	v_xor_b32_e32 v44, v18, v26
	v_xor_b32_e32 v46, v19, v27
	v_lshrrev_b32_e32 v28, 21, v40
	v_lshrrev_b32_e32 v29, 21, v42
	v_lshrrev_b32_e32 v30, 21, v44
	v_lshrrev_b32_e32 v31, 21, v46
	v_cmp_lt_u32_e64 s[0:1], s24, v28
	v_cmp_lt_u32_e64 s[10:11], s24, v29
	v_cmp_lt_u32_e64 s[16:17], s24, v30
	v_cmp_lt_u32_e64 s[66:67], s24, v31
	v_mbcnt_lo_u32_b32 v32, s0, 0
	v_mbcnt_lo_u32_b32 v33, s10, 0
	v_mbcnt_lo_u32_b32 v34, s16, 0
	v_mbcnt_lo_u32_b32 v35, s66, 0
	v_mbcnt_hi_u32_b32 v32, s1, v32
	v_mbcnt_hi_u32_b32 v33, s11, v33
	v_mbcnt_hi_u32_b32 v34, s17, v34
	v_mbcnt_hi_u32_b32 v35, s67, v35
	s_bcnt1_i32_b64 s98, s[0:1]
	s_bcnt1_i32_b64 s99, s[10:11]
	s_bcnt1_i32_b64 s100, s[16:17]
	s_bcnt1_i32_b64 s101, s[66:67]
	s_add_i32 s98, s98, s27
	s_add_i32 s99, s99, s98
	s_add_i32 s100, s100, s99
	v_add_u32_e32 v32, s27, v32
	s_add_i32 s27, s101, s100
	v_add_u32_e32 v33, s98, v33
	v_add_u32_e32 v34, s99, v34
	v_add_u32_e32 v35, s100, v35
	v_mad_i32_i24 v32, v32, v12, v13
	v_mad_i32_i24 v33, v33, v12, v13
	v_mad_i32_i24 v34, v34, v12, v13
	v_mad_i32_i24 v35, v35, v12, v13
	s_mov_b64 exec, s[0:1]
	ds_write_b32 v32, v41
	s_mov_b64 exec, s[10:11]
	ds_write_b32 v33, v43
	s_mov_b64 exec, s[16:17]
	ds_write_b32 v34, v45
	s_mov_b64 exec, s[66:67]
	ds_write_b32 v35, v47
	s_mov_b64 exec, s[14:15]
	v_cmp_eq_u32_e64 s[0:1], s24, v28
	v_cmp_eq_u32_e64 s[10:11], s24, v29
	v_cmp_eq_u32_e64 s[16:17], s24, v30
	v_cmp_eq_u32_e64 s[66:67], s24, v31
	s_and_b64 s[0:1], s[0:1], s[6:7]
	s_and_b64 s[10:11], s[10:11], s[6:7]
	s_and_b64 s[16:17], s[16:17], s[6:7]
	s_and_b64 s[66:67], s[66:67], s[6:7]
	v_mbcnt_lo_u32_b32 v36, s0, 0
	v_mbcnt_lo_u32_b32 v37, s10, 0
	v_mbcnt_lo_u32_b32 v38, s16, 0
	v_mbcnt_lo_u32_b32 v39, s66, 0
	v_mbcnt_hi_u32_b32 v36, s1, v36
	v_mbcnt_hi_u32_b32 v37, s11, v37
	v_mbcnt_hi_u32_b32 v38, s17, v38
	v_mbcnt_hi_u32_b32 v39, s67, v39
	s_bcnt1_i32_b64 s98, s[0:1]
	s_bcnt1_i32_b64 s99, s[10:11]
	s_bcnt1_i32_b64 s100, s[16:17]
	s_bcnt1_i32_b64 s101, s[66:67]
	s_add_i32 s98, s98, s28
	s_add_i32 s99, s99, s98
	s_add_i32 s100, s100, s99
	v_add_u32_e32 v36, s28, v36
	s_add_i32 s28, s101, s100
	v_add_u32_e32 v37, s98, v37
	v_add_u32_e32 v38, s99, v38
	v_add_u32_e32 v39, s100, v39
	v_mad_i32_i24 v36, v36, v48, v14
	v_mad_i32_i24 v37, v37, v48, v14
	v_mad_i32_i24 v38, v38, v48, v14
	v_mad_i32_i24 v39, v39, v48, v14
	s_mov_b64 exec, s[0:1]
	ds_write_b64 v36, v[40:41]
	s_mov_b64 exec, s[10:11]
	ds_write_b64 v37, v[42:43]
	s_mov_b64 exec, s[16:17]
	ds_write_b64 v38, v[44:45]
	s_mov_b64 exec, s[66:67]
	ds_write_b64 v39, v[46:47]
	s_mov_b64 exec, s[14:15]
	v_add_u32_e32 v41, 0x100, v41
	v_cmp_gt_u32_e64 s[0:1], s26, v41
	s_and_b64 exec, exec, s[0:1]
	s_waitcnt lgkmcnt(8)
	s_cbranch_execnz .Lcls_loop
